# P5 residual epilogue: x rows prefetched 5 steps ahead into a ring of dead fragment registers; counted vmcnt instead of vmcnt(0) per step
# speedup vs baseline: 1.0020x; 1.0020x over previous
; __device__ __forceinline__ unsigned cvt_pk_bf16(float lo, float hi) { unsigned r; asm volatile("v_cvt_pk_bf16_f32 %0, %1, %2" : "=v"(r) : "v"(lo), "v"(hi)); return r; }
;     __device__ __forceinline__ void operator()(const f32x4 (&acc)[2][2][4][2], const Unit& u, int wr, int wc, int fr, int fq) const {
;     ...
;             for (int m = 0; m < 4; ++m) { const int r = u.pm * BM + ai * HALF + wr * 64 + m * 16 + fr; float ss = 0.f;
; #pragma unroll
;                 for (int bj = 0; bj < 2; ++bj) { const int c8 = u.pn * BM + bj * HALF + wc * 32 + 8 * fq; const size_t off = (size_t)r * ldc + c8;
;                     float b[8];
;                     if (BF) { const u32x4 w = *(const u32x4*)((const bf16_t*)base + off); b[0] = bflo(w.x); b[1] = bfhi(w.x); b[2] = bflo(w.y); b[3] = bfhi(w.y); b[4] = bflo(w.z); b[5] = bfhi(w.z); b[6] = bflo(w.w); b[7] = bfhi(w.w); }
;                     else { const f32x4 b0 = __builtin_nontemporal_load((const f32x4*)((const float*)base + off)), b1 = __builtin_nontemporal_load((const f32x4*)((const float*)base + off + 4)); b[0] = b0[0]; b[1] = b0[1]; b[2] = b0[2]; b[3] = b0[3]; b[4] = b1[0]; b[5] = b1[1]; b[6] = b1[2]; b[7] = b1[3]; }
;                     float h[8];
; #pragma unroll
;                     for (int j = 0; j < 4; ++j) { h[j] = b[j] + acc[ai][bj][m][0][j]; h[4 + j] = b[4 + j] + acc[ai][bj][m][1][j]; }
; #pragma unroll
;                     for (int j = 0; j < 8; ++j) ss += h[j] * h[j];
;                     u32x4 w; w.x = cvt_pk_bf16(h[0], h[1]); w.y = cvt_pk_bf16(h[2], h[3]); w.z = cvt_pk_bf16(h[4], h[5]); w.w = cvt_pk_bf16(h[6], h[7]);
;                     *(u32x4*)(Hb + off) = w; }
;                 ss += __shfl_xor(ss, 16); ss += __shfl_xor(ss, 32);
;                 if (fq == 0) unsafeAtomicAdd(sumsq + r, ss); }
.LBB0_1608:
	s_lshl_b32 s2, s62, 8
	v_mov_b32_e32 v146, v1
	v_mov_b32_e32 v172, v152
	s_add_i32 s2, s2, s54
	s_nop 0
	v_add_u32_e32 v148, s2, v146
	s_lshl_b32 s2, s61, 8
	s_or_b32 s2, s2, s55
	v_lshl_add_u32 v146, v172, 3, s2
	v_ashrrev_i32_e32 v149, 31, v148
	v_lshlrev_b64 v[166:167], 11, v[148:149]
	v_ashrrev_i32_e32 v147, 31, v146
	v_lshl_add_u64 v[168:169], v[166:167], 0, v[146:147]
	s_waitcnt lgkmcnt(0)
	v_lshl_add_u64 v[150:151], v[168:169], 2, s[14:15]
	v_mov_b32_e32 v252, v150
	v_mov_b32_e32 v253, v151
	s_mov_b32 s99, 0
	s_mov_b32 s98, 0x0
	v_lshl_add_u64 v[254:255], v[252:253], 0, s[98:99]
	global_load_dwordx4 v[176:179], v[254:255], off nt
	global_load_dwordx4 v[184:187], v[254:255], off offset:16 nt
	s_mov_b32 s98, 0x200
	v_lshl_add_u64 v[254:255], v[252:253], 0, s[98:99]
	global_load_dwordx4 v[188:191], v[254:255], off nt
	global_load_dwordx4 v[192:195], v[254:255], off offset:16 nt
	s_mov_b32 s98, 0x20000
	v_lshl_add_u64 v[254:255], v[252:253], 0, s[98:99]
	global_load_dwordx4 v[200:203], v[254:255], off nt
	global_load_dwordx4 v[204:207], v[254:255], off offset:16 nt
	s_mov_b32 s98, 0x20200
	v_lshl_add_u64 v[254:255], v[252:253], 0, s[98:99]
	global_load_dwordx4 v[208:211], v[254:255], off nt
	global_load_dwordx4 v[212:215], v[254:255], off offset:16 nt
	s_mov_b32 s98, 0x40000
	v_lshl_add_u64 v[254:255], v[252:253], 0, s[98:99]
	global_load_dwordx4 v[218:221], v[254:255], off nt
	global_load_dwordx4 v[222:225], v[254:255], off offset:16 nt
	s_mov_b32 s98, 0x40200
	v_lshl_add_u64 v[254:255], v[252:253], 0, s[98:99]
	global_load_dwordx4 v[226:229], v[254:255], off nt
	global_load_dwordx4 v[230:233], v[254:255], off offset:16 nt
	s_waitcnt vmcnt(10)
	v_mov_b32_e32 v158, v176
	v_mov_b32_e32 v159, v177
	v_mov_b32_e32 v160, v178
	v_mov_b32_e32 v161, v179
	v_mov_b32_e32 v162, v184
	v_mov_b32_e32 v163, v185
	v_mov_b32_e32 v164, v186
	v_mov_b32_e32 v165, v187
	s_mov_b32 s98, 0x60000
	v_lshl_add_u64 v[254:255], v[252:253], 0, s[98:99]
	global_load_dwordx4 v[176:179], v[254:255], off nt
	global_load_dwordx4 v[184:187], v[254:255], off offset:16 nt
	v_add_u32_e32 v150, 0x80, v146
	v_ashrrev_i32_e32 v151, 31, v150
	v_lshl_add_u64 v[166:167], v[166:167], 0, v[150:151]
	v_lshl_add_u64 v[168:169], v[168:169], 1, s[20:21]
	v_lshl_add_u64 v[170:171], v[166:167], 2, s[14:15]
	v_cmp_eq_u32_e32 vcc, 0, v172
	v_add_f32_e32 v173, v122, v158
	v_add_f32_e32 v162, v126, v162
	v_add_f32_e32 v174, v123, v159
	v_add_f32_e32 v163, v127, v163
	v_add_f32_e32 v175, v124, v160
	v_add_f32_e32 v128, v128, v164
	v_add_f32_e32 v164, v125, v161
	v_add_f32_e32 v129, v129, v165
	v_cvt_pk_bf16_f32 v122, v173, v174
	v_cvt_pk_bf16_f32 v123, v175, v164
	v_cvt_pk_bf16_f32 v124, v162, v163
	v_cvt_pk_bf16_f32 v125, v128, v129
	global_store_dwordx4 v[168:169], v[122:125], off
	s_waitcnt vmcnt(11)
	v_mov_b32_e32 v124, v188
	v_mov_b32_e32 v125, v189
	v_mov_b32_e32 v126, v190
	v_mov_b32_e32 v127, v191
	s_nop 0
	v_mov_b32_e32 v158, v192
	v_mov_b32_e32 v159, v193
	v_mov_b32_e32 v160, v194
	v_mov_b32_e32 v161, v195
	s_mov_b32 s98, 0x60200
	v_lshl_add_u64 v[254:255], v[252:253], 0, s[98:99]
	global_load_dwordx4 v[188:191], v[254:255], off nt
	global_load_dwordx4 v[192:195], v[254:255], off offset:16 nt
	v_mul_f32_e32 v168, v174, v174
	v_fmac_f32_e32 v168, v173, v173
	v_fmac_f32_e32 v168, v175, v175
	v_fmac_f32_e32 v168, v164, v164
	v_fmac_f32_e32 v168, v162, v162
	v_fmac_f32_e32 v168, v163, v163
	v_fmac_f32_e32 v168, v128, v128
	v_fmac_f32_e32 v168, v129, v129
	v_and_b32_e32 v123, 64, v157
	v_xor_b32_e32 v122, 16, v157
	v_add_u32_e32 v123, 64, v123
	v_cmp_lt_i32_e64 s[8:9], v122, v123
	v_xor_b32_e32 v165, 32, v157
	v_add_f32_e32 v118, v118, v124
	v_add_f32_e32 v124, v114, v158
	v_add_f32_e32 v114, v119, v125
	v_fmac_f32_e32 v168, v118, v118
	v_add_f32_e32 v125, v115, v159
	v_add_f32_e32 v115, v120, v126
	v_fmac_f32_e32 v168, v114, v114
	v_add_f32_e32 v126, v116, v160
	v_add_f32_e32 v116, v121, v127
	v_fmac_f32_e32 v168, v115, v115
	v_fmac_f32_e32 v168, v116, v116
	v_fmac_f32_e32 v168, v124, v124
	v_fmac_f32_e32 v168, v125, v125
	v_cndmask_b32_e64 v122, v157, v122, s[8:9]
	v_add_f32_e32 v117, v117, v161
	v_fmac_f32_e32 v168, v126, v126
	v_lshlrev_b32_e32 v122, 2, v122
	v_fmac_f32_e32 v168, v117, v117
	ds_bpermute_b32 v120, v122, v168
	v_cmp_lt_i32_e64 s[8:9], v165, v123
	v_cvt_pk_bf16_f32 v118, v118, v114
	v_cvt_pk_bf16_f32 v119, v115, v116
	s_waitcnt lgkmcnt(0)
	v_add_f32_e32 v114, v168, v120
	v_cndmask_b32_e64 v121, v157, v165, s[8:9]
	v_lshlrev_b32_e32 v116, 2, v121
	ds_bpermute_b32 v115, v116, v114
	v_cvt_pk_bf16_f32 v120, v124, v125
	v_lshl_add_u64 v[124:125], v[166:167], 1, s[20:21]
	v_cvt_pk_bf16_f32 v121, v126, v117
	global_store_dwordx4 v[124:125], v[118:121], off
	s_and_saveexec_b64 s[8:9], vcc
	s_cbranch_execz .LBB0_1610
	v_lshl_add_u64 v[118:119], v[148:149], 2, s[18:19]
	s_waitcnt lgkmcnt(0)
	v_add_f32_e32 v114, v114, v115
	global_atomic_add_f32 v[118:119], v114, off
; __device__ __forceinline__ unsigned cvt_pk_bf16(float lo, float hi) { unsigned r; asm volatile("v_cvt_pk_bf16_f32 %0, %1, %2" : "=v"(r) : "v"(lo), "v"(hi)); return r; }
;     __device__ __forceinline__ void operator()(const f32x4 (&acc)[2][2][4][2], const Unit& u, int wr, int wc, int fr, int fq) const {
;     ...
;             for (int m = 0; m < 4; ++m) { const int r = u.pm * BM + ai * HALF + wr * 64 + m * 16 + fr; float ss = 0.f;
; #pragma unroll
;                 for (int bj = 0; bj < 2; ++bj) { const int c8 = u.pn * BM + bj * HALF + wc * 32 + 8 * fq; const size_t off = (size_t)r * ldc + c8;
;                     float b[8];
;                     if (BF) { const u32x4 w = *(const u32x4*)((const bf16_t*)base + off); b[0] = bflo(w.x); b[1] = bfhi(w.x); b[2] = bflo(w.y); b[3] = bfhi(w.y); b[4] = bflo(w.z); b[5] = bfhi(w.z); b[6] = bflo(w.w); b[7] = bfhi(w.w); }
;                     else { const f32x4 b0 = __builtin_nontemporal_load((const f32x4*)((const float*)base + off)), b1 = __builtin_nontemporal_load((const f32x4*)((const float*)base + off + 4)); b[0] = b0[0]; b[1] = b0[1]; b[2] = b0[2]; b[3] = b0[3]; b[4] = b1[0]; b[5] = b1[1]; b[6] = b1[2]; b[7] = b1[3]; }
;                     float h[8];
; #pragma unroll
;                     for (int j = 0; j < 4; ++j) { h[j] = b[j] + acc[ai][bj][m][0][j]; h[4 + j] = b[4 + j] + acc[ai][bj][m][1][j]; }
; #pragma unroll
;                     for (int j = 0; j < 8; ++j) ss += h[j] * h[j];
;                     u32x4 w; w.x = cvt_pk_bf16(h[0], h[1]); w.y = cvt_pk_bf16(h[2], h[3]); w.z = cvt_pk_bf16(h[4], h[5]); w.w = cvt_pk_bf16(h[6], h[7]);
;                     *(u32x4*)(Hb + off) = w; }
;                 ss += __shfl_xor(ss, 16); ss += __shfl_xor(ss, 32);
;                 if (fq == 0) unsafeAtomicAdd(sumsq + r, ss); }
.LBB0_1610:
	s_or_b64 exec, exec, s[8:9]
	v_add_u32_e32 v114, 16, v148
	s_waitcnt lgkmcnt(0)
	v_ashrrev_i32_e32 v115, 31, v114
	v_lshlrev_b64 v[128:129], 11, v[114:115]
	v_lshl_add_u64 v[158:159], v[128:129], 0, v[146:147]
	v_lshl_add_u64 v[124:125], v[158:159], 2, s[14:15]
	s_waitcnt vmcnt(12)
	v_mov_b32_e32 v118, v200
	v_mov_b32_e32 v119, v201
	v_mov_b32_e32 v120, v202
	v_mov_b32_e32 v121, v203
	s_nop 0
	v_mov_b32_e32 v124, v204
	v_mov_b32_e32 v125, v205
	v_mov_b32_e32 v126, v206
	v_mov_b32_e32 v127, v207
	s_mov_b32 s98, 0x100000
	v_lshl_add_u64 v[254:255], v[252:253], 0, s[98:99]
	global_load_dwordx4 v[200:203], v[254:255], off nt
	global_load_dwordx4 v[204:207], v[254:255], off offset:16 nt
	v_lshl_add_u64 v[128:129], v[128:129], 0, v[150:151]
	v_lshl_add_u64 v[158:159], v[158:159], 1, s[20:21]
	v_lshl_add_u64 v[160:161], v[128:129], 2, s[14:15]
	v_add_f32_e32 v117, v110, v118
	v_add_f32_e32 v118, v106, v124
	v_add_f32_e32 v119, v111, v119
	v_add_f32_e32 v123, v107, v125
	v_add_f32_e32 v120, v112, v120
	v_add_f32_e32 v124, v108, v126
	v_add_f32_e32 v121, v113, v121
	v_add_f32_e32 v125, v109, v127
	v_cvt_pk_bf16_f32 v106, v117, v119
	v_cvt_pk_bf16_f32 v107, v120, v121
	v_cvt_pk_bf16_f32 v108, v118, v123
	v_cvt_pk_bf16_f32 v109, v124, v125
	global_store_dwordx4 v[158:159], v[106:109], off
	s_waitcnt vmcnt(13)
	v_mov_b32_e32 v106, v208
	v_mov_b32_e32 v107, v209
	v_mov_b32_e32 v108, v210
	v_mov_b32_e32 v109, v211
	s_nop 0
	v_mov_b32_e32 v110, v212
	v_mov_b32_e32 v111, v213
	v_mov_b32_e32 v112, v214
	v_mov_b32_e32 v113, v215
	s_mov_b32 s98, 0x100200
	v_lshl_add_u64 v[254:255], v[252:253], 0, s[98:99]
	global_load_dwordx4 v[208:211], v[254:255], off nt
	global_load_dwordx4 v[212:215], v[254:255], off offset:16 nt
	v_mul_f32_e32 v119, v119, v119
	v_fmac_f32_e32 v119, v117, v117
	v_fmac_f32_e32 v119, v120, v120
	v_fmac_f32_e32 v119, v121, v121
	v_fmac_f32_e32 v119, v118, v118
	v_fmac_f32_e32 v119, v123, v123
	v_fmac_f32_e32 v119, v124, v124
	v_fmac_f32_e32 v119, v125, v125
	v_add_f32_e32 v102, v102, v106
	v_add_f32_e32 v106, v98, v110
	v_add_f32_e32 v98, v103, v107
	v_fmac_f32_e32 v119, v102, v102
	v_add_f32_e32 v103, v99, v111
	v_add_f32_e32 v99, v104, v108
	v_fmac_f32_e32 v119, v98, v98
	v_add_f32_e32 v105, v105, v109
	v_fmac_f32_e32 v119, v99, v99
	v_fmac_f32_e32 v119, v105, v105
	v_fmac_f32_e32 v119, v106, v106
	v_add_f32_e32 v104, v100, v112
	v_fmac_f32_e32 v119, v103, v103
	v_add_f32_e32 v107, v101, v113
	v_fmac_f32_e32 v119, v104, v104
	v_fmac_f32_e32 v119, v107, v107
	ds_bpermute_b32 v108, v122, v119
	v_cvt_pk_bf16_f32 v100, v102, v98
	v_cvt_pk_bf16_f32 v101, v99, v105
	v_cvt_pk_bf16_f32 v102, v106, v103
	v_cvt_pk_bf16_f32 v103, v104, v107
	s_waitcnt lgkmcnt(0)
	v_add_f32_e32 v98, v119, v108
	ds_bpermute_b32 v99, v116, v98
	v_lshl_add_u64 v[104:105], v[128:129], 1, s[20:21]
	global_store_dwordx4 v[104:105], v[100:103], off
	s_and_saveexec_b64 s[8:9], vcc
	s_cbranch_execz .LBB0_1612
	v_lshl_add_u64 v[100:101], v[114:115], 2, s[18:19]
	s_waitcnt lgkmcnt(0)
	v_add_f32_e32 v98, v98, v99
	global_atomic_add_f32 v[100:101], v98, off
.LBB0_1612:
	s_or_b64 exec, exec, s[8:9]
	v_add_u32_e32 v98, 32, v148
	s_waitcnt lgkmcnt(0)
	v_ashrrev_i32_e32 v99, 31, v98
	v_lshlrev_b64 v[108:109], 11, v[98:99]
	v_lshl_add_u64 v[110:111], v[108:109], 0, v[146:147]
	v_lshl_add_u64 v[104:105], v[110:111], 2, s[14:15]
	s_waitcnt vmcnt(14)
	v_mov_b32_e32 v100, v218
	v_mov_b32_e32 v101, v219
	v_mov_b32_e32 v102, v220
	v_mov_b32_e32 v103, v221
	s_nop 0
	v_mov_b32_e32 v104, v222
	v_mov_b32_e32 v105, v223
	v_mov_b32_e32 v106, v224
	v_mov_b32_e32 v107, v225
	s_mov_b32 s98, 0x120000
	v_lshl_add_u64 v[254:255], v[252:253], 0, s[98:99]
	global_load_dwordx4 v[218:221], v[254:255], off nt
	global_load_dwordx4 v[222:225], v[254:255], off offset:16 nt
	v_lshl_add_u64 v[108:109], v[108:109], 0, v[150:151]
	v_lshl_add_u64 v[110:111], v[110:111], 1, s[20:21]
	v_lshl_add_u64 v[112:113], v[108:109], 2, s[14:15]
	v_add_f32_e32 v100, v94, v100
	v_add_f32_e32 v104, v90, v104
	v_add_f32_e32 v101, v95, v101
	v_add_f32_e32 v105, v91, v105
	v_add_f32_e32 v102, v96, v102
	v_add_f32_e32 v106, v92, v106
	v_add_f32_e32 v103, v97, v103
	v_add_f32_e32 v107, v93, v107
	v_cvt_pk_bf16_f32 v90, v100, v101
	v_cvt_pk_bf16_f32 v91, v102, v103
	v_cvt_pk_bf16_f32 v92, v104, v105
	v_cvt_pk_bf16_f32 v93, v106, v107
	global_store_dwordx4 v[110:111], v[90:93], off
	s_waitcnt vmcnt(15)
	v_mov_b32_e32 v90, v226
	v_mov_b32_e32 v91, v227
	v_mov_b32_e32 v92, v228
	v_mov_b32_e32 v93, v229
	s_nop 0
	v_mov_b32_e32 v94, v230
	v_mov_b32_e32 v95, v231
	v_mov_b32_e32 v96, v232
	v_mov_b32_e32 v97, v233
	s_mov_b32 s98, 0x120200
	v_lshl_add_u64 v[254:255], v[252:253], 0, s[98:99]
	global_load_dwordx4 v[226:229], v[254:255], off nt
	global_load_dwordx4 v[230:233], v[254:255], off offset:16 nt
	v_mul_f32_e32 v101, v101, v101
	v_fmac_f32_e32 v101, v100, v100
	v_fmac_f32_e32 v101, v102, v102
	v_fmac_f32_e32 v101, v103, v103
	v_fmac_f32_e32 v101, v104, v104
	v_fmac_f32_e32 v101, v105, v105
	v_fmac_f32_e32 v101, v106, v106
	v_fmac_f32_e32 v101, v107, v107
	v_add_f32_e32 v86, v86, v90
	v_add_f32_e32 v90, v82, v94
	v_add_f32_e32 v82, v87, v91
	v_fmac_f32_e32 v101, v86, v86
	v_add_f32_e32 v87, v83, v95
	v_add_f32_e32 v83, v88, v92
	v_fmac_f32_e32 v101, v82, v82
	v_add_f32_e32 v89, v89, v93
	v_fmac_f32_e32 v101, v83, v83
	v_fmac_f32_e32 v101, v89, v89
	v_fmac_f32_e32 v101, v90, v90
	v_add_f32_e32 v88, v84, v96
	v_fmac_f32_e32 v101, v87, v87
	v_add_f32_e32 v91, v85, v97
	v_fmac_f32_e32 v101, v88, v88
	v_fmac_f32_e32 v101, v91, v91
	ds_bpermute_b32 v92, v122, v101
	v_cvt_pk_bf16_f32 v84, v86, v82
	v_cvt_pk_bf16_f32 v85, v83, v89
	v_cvt_pk_bf16_f32 v86, v90, v87
	v_cvt_pk_bf16_f32 v87, v88, v91
	s_waitcnt lgkmcnt(0)
	v_add_f32_e32 v82, v101, v92
	ds_bpermute_b32 v83, v116, v82
	v_lshl_add_u64 v[88:89], v[108:109], 1, s[20:21]
	global_store_dwordx4 v[88:89], v[84:87], off
	s_and_saveexec_b64 s[8:9], vcc
	s_cbranch_execz .LBB0_1614
	v_lshl_add_u64 v[84:85], v[98:99], 2, s[18:19]
	s_waitcnt lgkmcnt(0)
	v_add_f32_e32 v82, v82, v83
	global_atomic_add_f32 v[84:85], v82, off
; __device__ __forceinline__ unsigned cvt_pk_bf16(float lo, float hi) { unsigned r; asm volatile("v_cvt_pk_bf16_f32 %0, %1, %2" : "=v"(r) : "v"(lo), "v"(hi)); return r; }
;     __device__ __forceinline__ void operator()(const f32x4 (&acc)[2][2][4][2], const Unit& u, int wr, int wc, int fr, int fq) const {
;     ...
;             for (int m = 0; m < 4; ++m) { const int r = u.pm * BM + ai * HALF + wr * 64 + m * 16 + fr; float ss = 0.f;
; #pragma unroll
;                 for (int bj = 0; bj < 2; ++bj) { const int c8 = u.pn * BM + bj * HALF + wc * 32 + 8 * fq; const size_t off = (size_t)r * ldc + c8;
;                     float b[8];
;                     if (BF) { const u32x4 w = *(const u32x4*)((const bf16_t*)base + off); b[0] = bflo(w.x); b[1] = bfhi(w.x); b[2] = bflo(w.y); b[3] = bfhi(w.y); b[4] = bflo(w.z); b[5] = bfhi(w.z); b[6] = bflo(w.w); b[7] = bfhi(w.w); }
;                     else { const f32x4 b0 = __builtin_nontemporal_load((const f32x4*)((const float*)base + off)), b1 = __builtin_nontemporal_load((const f32x4*)((const float*)base + off + 4)); b[0] = b0[0]; b[1] = b0[1]; b[2] = b0[2]; b[3] = b0[3]; b[4] = b1[0]; b[5] = b1[1]; b[6] = b1[2]; b[7] = b1[3]; }
;                     float h[8];
; #pragma unroll
;                     for (int j = 0; j < 4; ++j) { h[j] = b[j] + acc[ai][bj][m][0][j]; h[4 + j] = b[4 + j] + acc[ai][bj][m][1][j]; }
; #pragma unroll
;                     for (int j = 0; j < 8; ++j) ss += h[j] * h[j];
;                     u32x4 w; w.x = cvt_pk_bf16(h[0], h[1]); w.y = cvt_pk_bf16(h[2], h[3]); w.z = cvt_pk_bf16(h[4], h[5]); w.w = cvt_pk_bf16(h[6], h[7]);
;                     *(u32x4*)(Hb + off) = w; }
;                 ss += __shfl_xor(ss, 16); ss += __shfl_xor(ss, 32);
;                 if (fq == 0) unsafeAtomicAdd(sumsq + r, ss); }
.LBB0_1614:
	s_or_b64 exec, exec, s[8:9]
	v_add_u32_e32 v82, 48, v148
	s_waitcnt lgkmcnt(0)
	v_ashrrev_i32_e32 v83, 31, v82
	v_lshlrev_b64 v[92:93], 11, v[82:83]
	v_lshl_add_u64 v[94:95], v[92:93], 0, v[146:147]
	v_lshl_add_u64 v[88:89], v[94:95], 2, s[14:15]
	s_waitcnt vmcnt(16)
	v_mov_b32_e32 v84, v176
	v_mov_b32_e32 v85, v177
	v_mov_b32_e32 v86, v178
	v_mov_b32_e32 v87, v179
	s_nop 0
	v_mov_b32_e32 v88, v184
	v_mov_b32_e32 v89, v185
	v_mov_b32_e32 v90, v186
	v_mov_b32_e32 v91, v187
	s_mov_b32 s98, 0x140000
	v_lshl_add_u64 v[254:255], v[252:253], 0, s[98:99]
	global_load_dwordx4 v[176:179], v[254:255], off nt
	global_load_dwordx4 v[184:187], v[254:255], off offset:16 nt
	v_lshl_add_u64 v[92:93], v[92:93], 0, v[150:151]
	v_lshl_add_u64 v[94:95], v[94:95], 1, s[20:21]
	v_lshl_add_u64 v[96:97], v[92:93], 2, s[14:15]
	v_add_f32_e32 v84, v78, v84
	v_add_f32_e32 v88, v74, v88
	v_add_f32_e32 v85, v79, v85
	v_add_f32_e32 v89, v75, v89
	v_add_f32_e32 v86, v80, v86
	v_add_f32_e32 v90, v76, v90
	v_add_f32_e32 v87, v81, v87
	v_add_f32_e32 v91, v77, v91
	v_cvt_pk_bf16_f32 v74, v84, v85
	v_cvt_pk_bf16_f32 v75, v86, v87
	v_cvt_pk_bf16_f32 v76, v88, v89
	v_cvt_pk_bf16_f32 v77, v90, v91
	global_store_dwordx4 v[94:95], v[74:77], off
	s_waitcnt vmcnt(16)
	v_mov_b32_e32 v74, v188
	v_mov_b32_e32 v75, v189
	v_mov_b32_e32 v76, v190
	v_mov_b32_e32 v77, v191
	s_nop 0
	v_mov_b32_e32 v78, v192
	v_mov_b32_e32 v79, v193
	v_mov_b32_e32 v80, v194
	v_mov_b32_e32 v81, v195
	s_mov_b32 s98, 0x140200
	v_lshl_add_u64 v[254:255], v[252:253], 0, s[98:99]
	global_load_dwordx4 v[188:191], v[254:255], off nt
	global_load_dwordx4 v[192:195], v[254:255], off offset:16 nt
	v_mul_f32_e32 v85, v85, v85
	v_fmac_f32_e32 v85, v84, v84
	v_fmac_f32_e32 v85, v86, v86
	v_fmac_f32_e32 v85, v87, v87
	v_fmac_f32_e32 v85, v88, v88
	v_fmac_f32_e32 v85, v89, v89
	v_fmac_f32_e32 v85, v90, v90
	v_fmac_f32_e32 v85, v91, v91
	v_add_f32_e32 v70, v70, v74
	v_add_f32_e32 v74, v66, v78
	v_add_f32_e32 v66, v71, v75
	v_fmac_f32_e32 v85, v70, v70
	v_add_f32_e32 v71, v67, v79
	v_add_f32_e32 v67, v72, v76
	v_fmac_f32_e32 v85, v66, v66
	v_add_f32_e32 v73, v73, v77
	v_fmac_f32_e32 v85, v67, v67
	v_fmac_f32_e32 v85, v73, v73
	v_fmac_f32_e32 v85, v74, v74
	v_add_f32_e32 v72, v68, v80
	v_fmac_f32_e32 v85, v71, v71
	v_add_f32_e32 v75, v69, v81
	v_fmac_f32_e32 v85, v72, v72
	v_fmac_f32_e32 v85, v75, v75
	ds_bpermute_b32 v76, v122, v85
	v_cvt_pk_bf16_f32 v68, v70, v66
	v_cvt_pk_bf16_f32 v69, v67, v73
	v_cvt_pk_bf16_f32 v70, v74, v71
	v_cvt_pk_bf16_f32 v71, v72, v75
	s_waitcnt lgkmcnt(0)
	v_add_f32_e32 v66, v85, v76
	ds_bpermute_b32 v67, v116, v66
	v_lshl_add_u64 v[72:73], v[92:93], 1, s[20:21]
	global_store_dwordx4 v[72:73], v[68:71], off
	s_and_saveexec_b64 s[8:9], vcc
	s_cbranch_execz .LBB0_1616
	v_lshl_add_u64 v[68:69], v[82:83], 2, s[18:19]
	s_waitcnt lgkmcnt(0)
	v_add_f32_e32 v66, v66, v67
	global_atomic_add_f32 v[68:69], v66, off
.LBB0_1616:
	s_or_b64 exec, exec, s[8:9]
	v_add_u32_e32 v66, 0x80, v148
	s_waitcnt lgkmcnt(0)
	v_ashrrev_i32_e32 v67, 31, v66
	v_lshlrev_b64 v[76:77], 11, v[66:67]
	v_lshl_add_u64 v[78:79], v[76:77], 0, v[146:147]
	v_lshl_add_u64 v[72:73], v[78:79], 2, s[14:15]
	s_waitcnt vmcnt(16)
	v_mov_b32_e32 v68, v200
	v_mov_b32_e32 v69, v201
	v_mov_b32_e32 v70, v202
	v_mov_b32_e32 v71, v203
	s_nop 0
	v_mov_b32_e32 v72, v204
	v_mov_b32_e32 v73, v205
	v_mov_b32_e32 v74, v206
	v_mov_b32_e32 v75, v207
	s_mov_b32 s98, 0x160000
	v_lshl_add_u64 v[254:255], v[252:253], 0, s[98:99]
	global_load_dwordx4 v[200:203], v[254:255], off nt
	global_load_dwordx4 v[204:207], v[254:255], off offset:16 nt
	v_lshl_add_u64 v[76:77], v[76:77], 0, v[150:151]
	v_lshl_add_u64 v[78:79], v[78:79], 1, s[20:21]
	v_lshl_add_u64 v[80:81], v[76:77], 2, s[14:15]
	v_add_f32_e32 v68, v62, v68
	v_add_f32_e32 v72, v58, v72
	v_add_f32_e32 v69, v63, v69
	v_add_f32_e32 v73, v59, v73
	v_add_f32_e32 v70, v64, v70
	v_add_f32_e32 v74, v60, v74
	v_add_f32_e32 v71, v65, v71
	v_add_f32_e32 v75, v61, v75
	v_cvt_pk_bf16_f32 v58, v68, v69
	v_cvt_pk_bf16_f32 v59, v70, v71
	v_cvt_pk_bf16_f32 v60, v72, v73
	v_cvt_pk_bf16_f32 v61, v74, v75
	global_store_dwordx4 v[78:79], v[58:61], off
	s_waitcnt vmcnt(16)
	v_mov_b32_e32 v58, v208
	v_mov_b32_e32 v59, v209
	v_mov_b32_e32 v60, v210
	v_mov_b32_e32 v61, v211
	s_nop 0
	v_mov_b32_e32 v62, v212
	v_mov_b32_e32 v63, v213
	v_mov_b32_e32 v64, v214
	v_mov_b32_e32 v65, v215
	s_mov_b32 s98, 0x160200
	v_lshl_add_u64 v[254:255], v[252:253], 0, s[98:99]
	global_load_dwordx4 v[208:211], v[254:255], off nt
	global_load_dwordx4 v[212:215], v[254:255], off offset:16 nt
	v_mul_f32_e32 v69, v69, v69
	v_fmac_f32_e32 v69, v68, v68
	v_fmac_f32_e32 v69, v70, v70
	v_fmac_f32_e32 v69, v71, v71
	v_fmac_f32_e32 v69, v72, v72
	v_fmac_f32_e32 v69, v73, v73
	v_fmac_f32_e32 v69, v74, v74
	v_fmac_f32_e32 v69, v75, v75
	v_add_f32_e32 v54, v54, v58
	v_add_f32_e32 v58, v50, v62
	v_add_f32_e32 v50, v55, v59
	v_fmac_f32_e32 v69, v54, v54
	v_add_f32_e32 v55, v51, v63
	v_add_f32_e32 v51, v56, v60
	v_fmac_f32_e32 v69, v50, v50
	v_add_f32_e32 v57, v57, v61
	v_fmac_f32_e32 v69, v51, v51
	v_fmac_f32_e32 v69, v57, v57
	v_fmac_f32_e32 v69, v58, v58
	v_add_f32_e32 v56, v52, v64
	v_fmac_f32_e32 v69, v55, v55
	v_add_f32_e32 v59, v53, v65
	v_fmac_f32_e32 v69, v56, v56
	v_fmac_f32_e32 v69, v59, v59
	ds_bpermute_b32 v60, v122, v69
	v_cvt_pk_bf16_f32 v52, v54, v50
	v_cvt_pk_bf16_f32 v53, v51, v57
	v_cvt_pk_bf16_f32 v54, v58, v55
	v_cvt_pk_bf16_f32 v55, v56, v59
	s_waitcnt lgkmcnt(0)
	v_add_f32_e32 v50, v69, v60
	ds_bpermute_b32 v51, v116, v50
	v_lshl_add_u64 v[56:57], v[76:77], 1, s[20:21]
	global_store_dwordx4 v[56:57], v[52:55], off
	s_and_saveexec_b64 s[8:9], vcc
	s_cbranch_execz .LBB0_1618
	v_lshl_add_u64 v[52:53], v[66:67], 2, s[18:19]
	s_waitcnt lgkmcnt(0)
	v_add_f32_e32 v50, v50, v51
	global_atomic_add_f32 v[52:53], v50, off
; __device__ __forceinline__ unsigned cvt_pk_bf16(float lo, float hi) { unsigned r; asm volatile("v_cvt_pk_bf16_f32 %0, %1, %2" : "=v"(r) : "v"(lo), "v"(hi)); return r; }
;     __device__ __forceinline__ void operator()(const f32x4 (&acc)[2][2][4][2], const Unit& u, int wr, int wc, int fr, int fq) const {
;     ...
;             for (int m = 0; m < 4; ++m) { const int r = u.pm * BM + ai * HALF + wr * 64 + m * 16 + fr; float ss = 0.f;
; #pragma unroll
;                 for (int bj = 0; bj < 2; ++bj) { const int c8 = u.pn * BM + bj * HALF + wc * 32 + 8 * fq; const size_t off = (size_t)r * ldc + c8;
;                     float b[8];
;                     if (BF) { const u32x4 w = *(const u32x4*)((const bf16_t*)base + off); b[0] = bflo(w.x); b[1] = bfhi(w.x); b[2] = bflo(w.y); b[3] = bfhi(w.y); b[4] = bflo(w.z); b[5] = bfhi(w.z); b[6] = bflo(w.w); b[7] = bfhi(w.w); }
;                     else { const f32x4 b0 = __builtin_nontemporal_load((const f32x4*)((const float*)base + off)), b1 = __builtin_nontemporal_load((const f32x4*)((const float*)base + off + 4)); b[0] = b0[0]; b[1] = b0[1]; b[2] = b0[2]; b[3] = b0[3]; b[4] = b1[0]; b[5] = b1[1]; b[6] = b1[2]; b[7] = b1[3]; }
;                     float h[8];
; #pragma unroll
;                     for (int j = 0; j < 4; ++j) { h[j] = b[j] + acc[ai][bj][m][0][j]; h[4 + j] = b[4 + j] + acc[ai][bj][m][1][j]; }
; #pragma unroll
;                     for (int j = 0; j < 8; ++j) ss += h[j] * h[j];
;                     u32x4 w; w.x = cvt_pk_bf16(h[0], h[1]); w.y = cvt_pk_bf16(h[2], h[3]); w.z = cvt_pk_bf16(h[4], h[5]); w.w = cvt_pk_bf16(h[6], h[7]);
;                     *(u32x4*)(Hb + off) = w; }
;                 ss += __shfl_xor(ss, 16); ss += __shfl_xor(ss, 32);
;                 if (fq == 0) unsafeAtomicAdd(sumsq + r, ss); }
.LBB0_1618:
	s_or_b64 exec, exec, s[8:9]
	v_add_u32_e32 v50, 0x90, v148
	s_waitcnt lgkmcnt(0)
	v_ashrrev_i32_e32 v51, 31, v50
	v_lshlrev_b64 v[60:61], 11, v[50:51]
	v_lshl_add_u64 v[62:63], v[60:61], 0, v[146:147]
	v_lshl_add_u64 v[56:57], v[62:63], 2, s[14:15]
	s_waitcnt vmcnt(16)
	v_mov_b32_e32 v52, v218
	v_mov_b32_e32 v53, v219
	v_mov_b32_e32 v54, v220
	v_mov_b32_e32 v55, v221
	s_nop 0
	v_mov_b32_e32 v56, v222
	v_mov_b32_e32 v57, v223
	v_mov_b32_e32 v58, v224
	v_mov_b32_e32 v59, v225
	v_lshl_add_u64 v[60:61], v[60:61], 0, v[150:151]
	v_lshl_add_u64 v[62:63], v[62:63], 1, s[20:21]
	v_lshl_add_u64 v[64:65], v[60:61], 2, s[14:15]
	v_add_f32_e32 v52, v46, v52
	v_add_f32_e32 v56, v42, v56
	v_add_f32_e32 v53, v47, v53
	v_add_f32_e32 v57, v43, v57
	v_add_f32_e32 v54, v48, v54
	v_add_f32_e32 v58, v44, v58
	v_add_f32_e32 v55, v49, v55
	v_add_f32_e32 v59, v45, v59
	v_cvt_pk_bf16_f32 v42, v52, v53
	v_cvt_pk_bf16_f32 v43, v54, v55
	v_cvt_pk_bf16_f32 v44, v56, v57
	v_cvt_pk_bf16_f32 v45, v58, v59
	global_store_dwordx4 v[62:63], v[42:45], off
	s_waitcnt vmcnt(14)
	v_mov_b32_e32 v42, v226
	v_mov_b32_e32 v43, v227
	v_mov_b32_e32 v44, v228
	v_mov_b32_e32 v45, v229
	s_nop 0
	v_mov_b32_e32 v46, v230
	v_mov_b32_e32 v47, v231
	v_mov_b32_e32 v48, v232
	v_mov_b32_e32 v49, v233
	v_mul_f32_e32 v53, v53, v53
	v_fmac_f32_e32 v53, v52, v52
	v_fmac_f32_e32 v53, v54, v54
	v_fmac_f32_e32 v53, v55, v55
	v_fmac_f32_e32 v53, v56, v56
	v_fmac_f32_e32 v53, v57, v57
	v_fmac_f32_e32 v53, v58, v58
	v_fmac_f32_e32 v53, v59, v59
	v_add_f32_e32 v38, v38, v42
	v_add_f32_e32 v42, v34, v46
	v_add_f32_e32 v34, v39, v43
	v_fmac_f32_e32 v53, v38, v38
	v_add_f32_e32 v39, v35, v47
	v_add_f32_e32 v35, v40, v44
	v_fmac_f32_e32 v53, v34, v34
	v_add_f32_e32 v41, v41, v45
	v_fmac_f32_e32 v53, v35, v35
	v_fmac_f32_e32 v53, v41, v41
	v_fmac_f32_e32 v53, v42, v42
	v_add_f32_e32 v40, v36, v48
	v_fmac_f32_e32 v53, v39, v39
	v_add_f32_e32 v43, v37, v49
	v_fmac_f32_e32 v53, v40, v40
	v_fmac_f32_e32 v53, v43, v43
	ds_bpermute_b32 v44, v122, v53
	v_cvt_pk_bf16_f32 v36, v38, v34
	v_cvt_pk_bf16_f32 v37, v35, v41
	v_cvt_pk_bf16_f32 v38, v42, v39
	v_cvt_pk_bf16_f32 v39, v40, v43
	s_waitcnt lgkmcnt(0)
	v_add_f32_e32 v34, v53, v44
	ds_bpermute_b32 v35, v116, v34
	v_lshl_add_u64 v[40:41], v[60:61], 1, s[20:21]
	global_store_dwordx4 v[40:41], v[36:39], off
	s_and_saveexec_b64 s[8:9], vcc
	s_cbranch_execz .LBB0_1620
	v_lshl_add_u64 v[36:37], v[50:51], 2, s[18:19]
	s_waitcnt lgkmcnt(0)
	v_add_f32_e32 v34, v34, v35
	global_atomic_add_f32 v[36:37], v34, off
; __device__ __forceinline__ unsigned cvt_pk_bf16(float lo, float hi) { unsigned r; asm volatile("v_cvt_pk_bf16_f32 %0, %1, %2" : "=v"(r) : "v"(lo), "v"(hi)); return r; }
;     __device__ __forceinline__ void operator()(const f32x4 (&acc)[2][2][4][2], const Unit& u, int wr, int wc, int fr, int fq) const {
;     ...
;             for (int m = 0; m < 4; ++m) { const int r = u.pm * BM + ai * HALF + wr * 64 + m * 16 + fr; float ss = 0.f;
; #pragma unroll
;                 for (int bj = 0; bj < 2; ++bj) { const int c8 = u.pn * BM + bj * HALF + wc * 32 + 8 * fq; const size_t off = (size_t)r * ldc + c8;
;                     float b[8];
;                     if (BF) { const u32x4 w = *(const u32x4*)((const bf16_t*)base + off); b[0] = bflo(w.x); b[1] = bfhi(w.x); b[2] = bflo(w.y); b[3] = bfhi(w.y); b[4] = bflo(w.z); b[5] = bfhi(w.z); b[6] = bflo(w.w); b[7] = bfhi(w.w); }
;                     else { const f32x4 b0 = __builtin_nontemporal_load((const f32x4*)((const float*)base + off)), b1 = __builtin_nontemporal_load((const f32x4*)((const float*)base + off + 4)); b[0] = b0[0]; b[1] = b0[1]; b[2] = b0[2]; b[3] = b0[3]; b[4] = b1[0]; b[5] = b1[1]; b[6] = b1[2]; b[7] = b1[3]; }
;                     float h[8];
; #pragma unroll
;                     for (int j = 0; j < 4; ++j) { h[j] = b[j] + acc[ai][bj][m][0][j]; h[4 + j] = b[4 + j] + acc[ai][bj][m][1][j]; }
; #pragma unroll
;                     for (int j = 0; j < 8; ++j) ss += h[j] * h[j];
;                     u32x4 w; w.x = cvt_pk_bf16(h[0], h[1]); w.y = cvt_pk_bf16(h[2], h[3]); w.z = cvt_pk_bf16(h[4], h[5]); w.w = cvt_pk_bf16(h[6], h[7]);
;                     *(u32x4*)(Hb + off) = w; }
;                 ss += __shfl_xor(ss, 16); ss += __shfl_xor(ss, 32);
;                 if (fq == 0) unsafeAtomicAdd(sumsq + r, ss); }
.LBB0_1620:
	s_or_b64 exec, exec, s[8:9]
	v_add_u32_e32 v34, 0xa0, v148
	s_waitcnt lgkmcnt(0)
	v_ashrrev_i32_e32 v35, 31, v34
	v_lshlrev_b64 v[44:45], 11, v[34:35]
	v_lshl_add_u64 v[46:47], v[44:45], 0, v[146:147]
	v_lshl_add_u64 v[40:41], v[46:47], 2, s[14:15]
	s_waitcnt vmcnt(12)
	v_mov_b32_e32 v36, v176
	v_mov_b32_e32 v37, v177
	v_mov_b32_e32 v38, v178
	v_mov_b32_e32 v39, v179
	s_nop 0
	v_mov_b32_e32 v40, v184
	v_mov_b32_e32 v41, v185
	v_mov_b32_e32 v42, v186
	v_mov_b32_e32 v43, v187
	v_lshl_add_u64 v[44:45], v[44:45], 0, v[150:151]
	v_lshl_add_u64 v[46:47], v[46:47], 1, s[20:21]
	v_lshl_add_u64 v[48:49], v[44:45], 2, s[14:15]
	v_add_f32_e32 v36, v30, v36
	v_add_f32_e32 v40, v26, v40
	v_add_f32_e32 v37, v31, v37
	v_add_f32_e32 v41, v27, v41
	v_add_f32_e32 v38, v32, v38
	v_add_f32_e32 v42, v28, v42
	v_add_f32_e32 v39, v33, v39
	v_add_f32_e32 v43, v29, v43
	v_cvt_pk_bf16_f32 v26, v36, v37
	v_cvt_pk_bf16_f32 v27, v38, v39
	v_cvt_pk_bf16_f32 v28, v40, v41
	v_cvt_pk_bf16_f32 v29, v42, v43
	global_store_dwordx4 v[46:47], v[26:29], off
	s_waitcnt vmcnt(10)
	v_mov_b32_e32 v26, v188
	v_mov_b32_e32 v27, v189
	v_mov_b32_e32 v28, v190
	v_mov_b32_e32 v29, v191
	s_nop 0
	v_mov_b32_e32 v30, v192
	v_mov_b32_e32 v31, v193
	v_mov_b32_e32 v32, v194
	v_mov_b32_e32 v33, v195
	v_mul_f32_e32 v37, v37, v37
	v_fmac_f32_e32 v37, v36, v36
	v_fmac_f32_e32 v37, v38, v38
	v_fmac_f32_e32 v37, v39, v39
	v_fmac_f32_e32 v37, v40, v40
	v_fmac_f32_e32 v37, v41, v41
	v_fmac_f32_e32 v37, v42, v42
	v_fmac_f32_e32 v37, v43, v43
	v_add_f32_e32 v22, v22, v26
	v_add_f32_e32 v26, v18, v30
	v_add_f32_e32 v18, v23, v27
	v_fmac_f32_e32 v37, v22, v22
	v_add_f32_e32 v23, v19, v31
	v_add_f32_e32 v19, v24, v28
	v_fmac_f32_e32 v37, v18, v18
	v_add_f32_e32 v25, v25, v29
	v_fmac_f32_e32 v37, v19, v19
	v_fmac_f32_e32 v37, v25, v25
	v_fmac_f32_e32 v37, v26, v26
	v_add_f32_e32 v24, v20, v32
	v_fmac_f32_e32 v37, v23, v23
	v_add_f32_e32 v27, v21, v33
	v_fmac_f32_e32 v37, v24, v24
	v_fmac_f32_e32 v37, v27, v27
	ds_bpermute_b32 v28, v122, v37
	v_cvt_pk_bf16_f32 v20, v22, v18
	v_cvt_pk_bf16_f32 v21, v19, v25
	v_cvt_pk_bf16_f32 v22, v26, v23
	v_cvt_pk_bf16_f32 v23, v24, v27
	s_waitcnt lgkmcnt(0)
	v_add_f32_e32 v18, v37, v28
	ds_bpermute_b32 v19, v116, v18
	v_lshl_add_u64 v[24:25], v[44:45], 1, s[20:21]
	global_store_dwordx4 v[24:25], v[20:23], off
	s_and_saveexec_b64 s[8:9], vcc
	s_cbranch_execz .LBB0_1622
	v_lshl_add_u64 v[20:21], v[34:35], 2, s[18:19]
	s_waitcnt lgkmcnt(0)
	v_add_f32_e32 v18, v18, v19
	global_atomic_add_f32 v[20:21], v18, off
.LBB0_1622:
	s_or_b64 exec, exec, s[8:9]
	v_add_u32_e32 v18, 0xb0, v148
	s_waitcnt lgkmcnt(0)
	v_ashrrev_i32_e32 v19, 31, v18
	v_lshlrev_b64 v[28:29], 11, v[18:19]
	v_lshl_add_u64 v[30:31], v[28:29], 0, v[146:147]
	v_lshl_add_u64 v[24:25], v[30:31], 2, s[14:15]
	s_waitcnt vmcnt(8)
	v_mov_b32_e32 v20, v200
	v_mov_b32_e32 v21, v201
	v_mov_b32_e32 v22, v202
	v_mov_b32_e32 v23, v203
	s_nop 0
	v_mov_b32_e32 v24, v204
	v_mov_b32_e32 v25, v205
	v_mov_b32_e32 v26, v206
	v_mov_b32_e32 v27, v207
	v_lshl_add_u64 v[28:29], v[28:29], 0, v[150:151]
	v_lshl_add_u64 v[30:31], v[30:31], 1, s[20:21]
	v_lshl_add_u64 v[32:33], v[28:29], 2, s[14:15]
	v_add_f32_e32 v20, v14, v20
	v_add_f32_e32 v24, v10, v24
	v_add_f32_e32 v21, v15, v21
	v_add_f32_e32 v25, v11, v25
	v_add_f32_e32 v22, v16, v22
	v_add_f32_e32 v26, v12, v26
	v_add_f32_e32 v23, v17, v23
	v_add_f32_e32 v27, v13, v27
	v_cvt_pk_bf16_f32 v10, v20, v21
	v_cvt_pk_bf16_f32 v11, v22, v23
	v_cvt_pk_bf16_f32 v12, v24, v25
	v_cvt_pk_bf16_f32 v13, v26, v27
	global_store_dwordx4 v[30:31], v[10:13], off
	s_waitcnt vmcnt(6)
	v_mov_b32_e32 v10, v208
	v_mov_b32_e32 v11, v209
	v_mov_b32_e32 v12, v210
	v_mov_b32_e32 v13, v211
	s_nop 0
	v_mov_b32_e32 v14, v212
	v_mov_b32_e32 v15, v213
	v_mov_b32_e32 v16, v214
	v_mov_b32_e32 v17, v215
	v_mul_f32_e32 v21, v21, v21
	v_fmac_f32_e32 v21, v20, v20
	v_fmac_f32_e32 v21, v22, v22
	v_fmac_f32_e32 v21, v23, v23
	v_fmac_f32_e32 v21, v24, v24
	v_fmac_f32_e32 v21, v25, v25
	v_fmac_f32_e32 v21, v26, v26
	v_fmac_f32_e32 v21, v27, v27
	v_add_f32_e32 v6, v6, v10
	v_add_f32_e32 v10, v2, v14
	v_add_f32_e32 v2, v7, v11
	v_fmac_f32_e32 v21, v6, v6
	v_add_f32_e32 v7, v3, v15
	v_add_f32_e32 v3, v8, v12
	v_fmac_f32_e32 v21, v2, v2
	v_add_f32_e32 v9, v9, v13
	v_fmac_f32_e32 v21, v3, v3
	v_fmac_f32_e32 v21, v9, v9
	v_fmac_f32_e32 v21, v10, v10
	v_add_f32_e32 v8, v4, v16
	v_fmac_f32_e32 v21, v7, v7
	v_add_f32_e32 v11, v5, v17
	v_fmac_f32_e32 v21, v8, v8
	v_fmac_f32_e32 v21, v11, v11
	ds_bpermute_b32 v12, v122, v21
	v_cvt_pk_bf16_f32 v4, v6, v2
	v_cvt_pk_bf16_f32 v5, v3, v9
	v_cvt_pk_bf16_f32 v6, v10, v7
	v_cvt_pk_bf16_f32 v7, v8, v11
	s_waitcnt lgkmcnt(0)
	v_add_f32_e32 v2, v21, v12
	ds_bpermute_b32 v3, v116, v2
	v_lshl_add_u64 v[8:9], v[28:29], 1, s[20:21]
	global_store_dwordx4 v[8:9], v[4:7], off
	s_and_saveexec_b64 s[8:9], vcc
	s_cbranch_execz .LBB0_1624
	v_lshl_add_u64 v[4:5], v[18:19], 2, s[18:19]
	s_waitcnt lgkmcnt(0)
	v_add_f32_e32 v2, v2, v3
	global_atomic_add_f32 v[4:5], v2, off

; __global__ void __launch_bounds__(NWAVES * 64, 2) hymba_fwd(Args args) {
	.amdhsa_kernel _Z9hymba_fwd4Args
		.amdhsa_group_segment_fixed_size 0
		.amdhsa_private_segment_fixed_size 0
		.amdhsa_kernarg_size 504
		.amdhsa_user_sgpr_count 2
		.amdhsa_user_sgpr_dispatch_ptr 0
		.amdhsa_user_sgpr_queue_ptr 0
		.amdhsa_user_sgpr_kernarg_segment_ptr 1
		.amdhsa_user_sgpr_dispatch_id 0
		.amdhsa_user_sgpr_kernarg_preload_length 0
		.amdhsa_user_sgpr_kernarg_preload_offset 0
		.amdhsa_user_sgpr_private_segment_size 0
		.amdhsa_uses_dynamic_stack 0
		.amdhsa_enable_private_segment 0
		.amdhsa_system_sgpr_workgroup_id_x 1
		.amdhsa_system_sgpr_workgroup_id_y 0
		.amdhsa_system_sgpr_workgroup_id_z 0
		.amdhsa_system_sgpr_workgroup_info 0
		.amdhsa_system_vgpr_workitem_id 0
		.amdhsa_next_free_vgpr 256
		.amdhsa_next_free_sgpr 100
		.amdhsa_accum_offset 256
		.amdhsa_reserve_vcc 1
		.amdhsa_float_round_mode_32 0
		.amdhsa_float_round_mode_16_64 0
		.amdhsa_float_denorm_mode_32 3
		.amdhsa_float_denorm_mode_16_64 3
		.amdhsa_dx10_clamp 1
		.amdhsa_ieee_mode 1
		.amdhsa_fp16_overflow 0
		.amdhsa_tg_split 0
		.amdhsa_exception_fp_ieee_invalid_op 0
		.amdhsa_exception_fp_denorm_src 0
		.amdhsa_exception_fp_ieee_div_zero 0
		.amdhsa_exception_fp_ieee_overflow 0
		.amdhsa_exception_fp_ieee_underflow 0
		.amdhsa_exception_fp_ieee_inexact 0
		.amdhsa_exception_int_div_zero 0
	.end_amdhsa_kernel

; __global__ void __launch_bounds__(NWAVES * 64, 2) hymba_fwd(Args args) {
amdhsa.kernels:
  - .agpr_count:     0
    .args:
      - .offset:         0
        .size:           248
        .value_kind:     by_value
      - .offset:         248
        .size:           4
        .value_kind:     hidden_block_count_x
      - .offset:         252
        .size:           4
        .value_kind:     hidden_block_count_y
      - .offset:         256
        .size:           4
        .value_kind:     hidden_block_count_z
      - .offset:         260
        .size:           2
        .value_kind:     hidden_group_size_x
      - .offset:         262
        .size:           2
        .value_kind:     hidden_group_size_y
      - .offset:         264
        .size:           2
        .value_kind:     hidden_group_size_z
      - .offset:         266
        .size:           2
        .value_kind:     hidden_remainder_x
      - .offset:         268
        .size:           2
        .value_kind:     hidden_remainder_y
      - .offset:         270
        .size:           2
        .value_kind:     hidden_remainder_z
      - .offset:         288
        .size:           8
        .value_kind:     hidden_global_offset_x
      - .offset:         296
        .size:           8
        .value_kind:     hidden_global_offset_y
      - .offset:         304
        .size:           8
        .value_kind:     hidden_global_offset_z
      - .offset:         312
        .size:           2
        .value_kind:     hidden_grid_dims
      - .offset:         368
        .size:           4
        .value_kind:     hidden_dynamic_lds_size
    .group_segment_fixed_size: 0
    .kernarg_segment_align: 8
    .kernarg_segment_size: 504
    .language:       OpenCL C
    .language_version:
      - 2
      - 0
    .max_flat_workgroup_size: 512
    .name:           _Z9hymba_fwd4Args
    .private_segment_fixed_size: 0
    .sgpr_count:     106
    .sgpr_spill_count: 26
    .symbol:         _Z9hymba_fwd4Args.kd
    .uniform_work_group_size: 1
    .uses_dynamic_stack: false
    .vgpr_count:     256
    .vgpr_spill_count: 0
    .wavefront_size: 64
